# attention K/V staging waits counted (vmcnt(k) keeps the 2-tiles-ahead loads in flight via an m0 flag) + no grid barrier between weight-prep step and layer-0 PREP (independent)
# speedup vs baseline: 1.0087x; 1.0087x over previous
; __global__ void __launch_bounds__(512, 2) mega(Args a) {
;     ...
;                 for (;;) {
;                     if (tid == 0) *s_unit = (int)atomicAdd(ctr, 1u);
;                     __syncthreads();
;                     const int u = *s_unit;
;                     __syncthreads();
;                     if (u >= nunits) break;
.LBB0_140:
	s_mov_b32 m0, 0
	s_and_saveexec_b64 s[14:15], s[62:63]
	s_cbranch_execz .LBB0_142
	v_readlane_b32 s4, v251, 6
	v_readlane_b32 s5, v251, 7
	s_nop 1
	v_mov_b64_e32 v[0:1], s[4:5]
	flat_atomic_add v0, v[0:1], v191 sc0
	v_readlane_b32 s4, v253, 26
	s_nop 1
	v_mov_b32_e32 v1, s4
	s_waitcnt vmcnt(0) lgkmcnt(0)
	ds_write_b32 v1, v0

.LBB0_153:
	s_add_i32 s24, s23, 1
	s_cmp_gt_i32 s24, 1
	s_cselect_b64 s[16:17], -1, 0
	s_cmp_lt_i32 s24, 2
	v_add_u32_e32 v2, s4, v129
	s_cbranch_scc1 .LBB0_158
	v_add_u32_e32 v0, 0xffffff40, v2
	v_ashrrev_i32_e32 v1, 31, v0
	v_lshlrev_b64 v[0:1], 11, v[0:1]
	v_lshl_add_u64 v[0:1], v[118:119], 0, v[0:1]
	global_load_dwordx4 v[110:113], v[0:1], off
	s_mov_b32 m0, 2
	s_and_saveexec_b64 s[18:19], s[44:45]
	s_cbranch_execz .LBB0_156
	v_add_u32_e32 v3, s4, v125
	v_add_u32_e32 v3, 0xffffff40, v3
	v_mad_i64_i32 v[38:39], s[20:21], v3, s81, v[120:121]
	global_load_dwordx4 v[106:109], v[38:39], off
	s_mov_b32 m0, 3

.LBB0_164:
	s_cmp_eq_u32 m0, 3
	s_cbranch_scc1 .Lmy_w3_1
	s_cmp_eq_u32 m0, 2
	s_cbranch_scc1 .Lmy_w2_1
	s_waitcnt vmcnt(0)
	s_branch .Lmy_wd_1
.Lmy_w3_1:
	s_waitcnt vmcnt(3)
	s_branch .Lmy_wd_1

.Lmy_wd_1:
	s_mov_b32 m0, 0
	ds_write_b128 v132, v[98:101] offset:13312
	s_and_saveexec_b64 s[18:19], s[44:45]
	v_add_u32_e32 v0, v126, v127
	ds_write_b128 v0, v[94:97] offset:13440
	s_or_b64 exec, exec, s[18:19]
	ds_write_b128 v133, v[102:105] offset:38912
.LBB0_167:
	s_cmp_lt_i32 s24, 3
	s_waitcnt lgkmcnt(0)
	s_barrier
	s_cbranch_scc1 .LBB0_172
	v_add_u32_e32 v0, 0xffffff00, v2
	v_ashrrev_i32_e32 v1, 31, v0
	v_lshlrev_b64 v[0:1], 11, v[0:1]
	v_lshl_add_u64 v[0:1], v[118:119], 0, v[0:1]
	global_load_dwordx4 v[98:101], v[0:1], off
	s_mov_b32 m0, 2
	s_and_saveexec_b64 s[18:19], s[44:45]
	s_cbranch_execz .LBB0_170
	v_add_u32_e32 v2, s4, v125
	v_add_u32_e32 v2, 0xffffff00, v2
	v_mad_i64_i32 v[2:3], s[20:21], v2, s81, v[120:121]
	global_load_dwordx4 v[94:97], v[2:3], off
	s_mov_b32 m0, 3

.Lmy_wd_2:
	s_mov_b32 m0, 0
	ds_write_b128 v132, v[110:113]
	s_and_saveexec_b64 s[16:17], s[44:45]
	v_add_u32_e32 v0, v126, v127
	ds_write_b128 v0, v[106:109] offset:128
	s_or_b64 exec, exec, s[16:17]
	ds_write_b128 v133, v[114:117] offset:26624

.LBB0_186:
	s_or_b64 exec, exec, s[16:17]
	v_add_u32_e32 v3, s5, v133
	ds_write_b128 v3, v[114:117] offset:26624

.LBB0_188:
	s_cmp_gt_u32 s23, 1
	s_cselect_b64 s[16:17], -1, 0
	s_cmp_lt_u32 s23, 2
	s_cselect_b64 s[14:15], -1, 0
	s_and_b64 vcc, exec, s[14:15]
	s_cbranch_vccnz .LBB0_193
	v_add_u32_e32 v38, 64, v2
	v_ashrrev_i32_e32 v39, 31, v38
	v_lshlrev_b64 v[38:39], 11, v[38:39]
	v_lshl_add_u64 v[38:39], v[118:119], 0, v[38:39]
	global_load_dwordx4 v[110:113], v[38:39], off
	s_mov_b32 m0, 2
	s_and_saveexec_b64 s[18:19], s[44:45]
	s_cbranch_execz .LBB0_191
	v_add_u32_e32 v3, 64, v138
	v_mad_i64_i32 v[40:41], s[20:21], v3, s81, v[0:1]
	global_load_dwordx4 v[106:109], v[40:41], off
	s_mov_b32 m0, 3

.LBB0_199:
	v_add_u32_e32 v3, s22, v132
	s_cmp_eq_u32 m0, 3
	s_cbranch_scc1 .Lmy_w3_3
	s_cmp_eq_u32 m0, 2
	s_cbranch_scc1 .Lmy_w2_3
	s_waitcnt vmcnt(0)
	s_branch .Lmy_wd_3

.Lmy_wd_3:
	s_mov_b32 m0, 0
	ds_write_b128 v3, v[98:101]
	s_and_saveexec_b64 s[18:19], s[44:45]
	ds_write_b128 v139, v[94:97] offset:128
	s_or_b64 exec, exec, s[18:19]
	v_add_u32_e32 v3, s24, v133
	ds_write_b128 v3, v[102:105] offset:26624
.LBB0_202:
	s_cmp_lt_u32 s23, 3
	s_waitcnt lgkmcnt(0)
	s_barrier
	s_cbranch_scc1 .LBB0_207
	v_ashrrev_i32_e32 v3, 31, v2
	v_lshlrev_b64 v[38:39], 11, v[2:3]
	v_lshl_add_u64 v[38:39], v[118:119], 0, v[38:39]
	global_load_dwordx4 v[98:101], v[38:39], off
	s_mov_b32 m0, 2
	s_and_saveexec_b64 s[18:19], s[44:45]
	s_cbranch_execz .LBB0_205
	v_mad_i64_i32 v[40:41], s[20:21], v138, s81, v[0:1]
	global_load_dwordx4 v[94:97], v[40:41], off
	s_mov_b32 m0, 3

.LBB0_213:
	v_add_u32_e32 v3, s4, v132
	s_cmp_eq_u32 m0, 3
	s_cbranch_scc1 .Lmy_w3_4
	s_cmp_eq_u32 m0, 2
	s_cbranch_scc1 .Lmy_w2_4
	s_waitcnt vmcnt(0)
	s_branch .Lmy_wd_4

.Lmy_wd_4:
	s_mov_b32 m0, 0
	ds_write_b128 v3, v[110:113]
	s_and_saveexec_b64 s[16:17], s[44:45]
	s_cbranch_execz .LBB0_186
	ds_write_b128 v140, v[106:109] offset:128
	s_branch .LBB0_186

.LBB0_220:
	s_cmp_gt_i32 s92, 1
	s_cselect_b64 s[14:15], -1, 0
	s_cmp_lt_i32 s92, 2
	s_cbranch_scc1 .LBB0_227
	s_lshl_b32 s4, s92, 6
	s_add_i32 s16, s4, 0xffffff80
	v_add_u32_e32 v4, s16, v177
	v_mad_i64_i32 v[0:1], s[4:5], v4, s81, v[146:147]
	v_add_u32_e32 v6, s16, v178
	v_mad_i64_i32 v[2:3], s[4:5], v6, s81, v[148:149]
	global_load_dwordx4 v[128:131], v[0:1], off
	global_load_dwordx4 v[132:135], v[2:3], off
	v_mad_i64_i32 v[0:1], s[4:5], v4, s81, v[150:151]
	v_mad_i64_i32 v[2:3], s[4:5], v6, s81, v[154:155]
	global_load_dwordx4 v[136:139], v[0:1], off
	global_load_dwordx4 v[140:143], v[2:3], off
	s_mov_b32 m0, 4
	s_cmp_gt_i32 s92, s84
	s_cbranch_scc0 .LBB0_228

.LBB0_223:
	s_cmp_eq_u32 m0, 0
	s_cbranch_scc1 .Lmy_wz_13
	s_waitcnt vmcnt(4)
	s_branch .Lmy_wd_13

.Lmy_wd_13:
	s_mov_b32 m0, 0
	ds_write_b128 v212, v[112:115] offset:17408
	ds_write_b128 v213, v[116:119] offset:17408
	ds_write_b128 v214, v[120:123] offset:55296
	ds_write_b128 v215, v[124:127] offset:55296
.LBB0_224:
	s_cmp_lt_i32 s92, 3
	s_waitcnt lgkmcnt(0)
	s_barrier
	s_cbranch_scc1 .LBB0_428
	s_lshl_b32 s4, s92, 6
	s_add_i32 s16, s4, 0xffffff40
	v_add_u32_e32 v4, s16, v177
	v_mad_i64_i32 v[0:1], s[4:5], v4, s81, v[146:147]
	v_add_u32_e32 v6, s16, v178
	v_mad_i64_i32 v[2:3], s[4:5], v6, s81, v[148:149]
	global_load_dwordx4 v[112:115], v[0:1], off
	global_load_dwordx4 v[116:119], v[2:3], off
	v_mad_i64_i32 v[0:1], s[4:5], v4, s81, v[150:151]
	v_mad_i64_i32 v[2:3], s[4:5], v6, s81, v[154:155]
	global_load_dwordx4 v[120:123], v[0:1], off
	global_load_dwordx4 v[124:127], v[2:3], off
	s_mov_b32 m0, 4
	s_add_i32 s4, s92, -1
	s_cmp_gt_i32 s4, s84
	s_cbranch_scc0 .LBB0_429

.Lmy_wd_14:
	s_mov_b32 m0, 0
	ds_write_b128 v212, v[128:131]
	ds_write_b128 v213, v[132:135]
	ds_write_b128 v214, v[136:139] offset:34816
	ds_write_b128 v215, v[140:143] offset:34816
	s_branch .LBB0_219

.LBB0_656:
	s_add_i32 s24, s22, 1
	s_cmp_gt_i32 s24, 1
	s_cselect_b64 s[16:17], -1, 0
	s_cmp_lt_i32 s24, 2
	v_add_u32_e32 v2, s53, v181
	v_add_u32_e32 v1, s53, v204
	v_add_u32_e32 v0, s53, v205
	s_cbranch_scc1 .LBB0_666
	v_add_u32_e32 v3, 0xffffff40, v2
	v_mad_i64_i32 v[6:7], s[18:19], v3, s81, v[156:157]
	v_add_u32_e32 v3, 0xffffff40, v1
	v_mad_i64_i32 v[8:9], s[18:19], v3, s81, v[158:159]
	v_add_u32_e32 v3, 0xffffff40, v0
	global_load_dwordx4 v[144:147], v[6:7], off
	global_load_dwordx4 v[140:143], v[8:9], off
	v_mad_i64_i32 v[6:7], s[18:19], v3, s81, v[160:161]
	global_load_dwordx4 v[148:151], v[6:7], off
	s_mov_b32 m0, 3
	s_add_i32 s23, s6, s22
	s_cmp_gt_i32 s24, s60
	s_cbranch_scc0 .LBB0_667

.LBB0_659:
	s_cmp_eq_u32 m0, 0
	s_cbranch_scc1 .Lmy_wz_5
	s_waitcnt vmcnt(3)
	s_branch .Lmy_wd_5

.Lmy_wd_5:
	s_mov_b32 m0, 0
	ds_write_b128 v165, v[128:131] offset:9216
	ds_write_b128 v178, v[132:135] offset:38912
	ds_write_b128 v179, v[136:139] offset:38912
.LBB0_660:
	s_cmp_lt_i32 s24, 3
	s_waitcnt lgkmcnt(0)
	s_barrier
	s_cbranch_scc1 .LBB0_672
	v_add_u32_e32 v2, 0xffffff00, v2
	v_add_u32_e32 v1, 0xffffff00, v1
	v_add_u32_e32 v0, 0xffffff00, v0
	v_mad_i64_i32 v[2:3], s[18:19], v2, s81, v[156:157]
	v_mad_i64_i32 v[6:7], s[18:19], v1, s81, v[158:159]
	v_mad_i64_i32 v[0:1], s[18:19], v0, s81, v[160:161]
	global_load_dwordx4 v[128:131], v[2:3], off
	global_load_dwordx4 v[132:135], v[6:7], off
	global_load_dwordx4 v[136:139], v[0:1], off
	s_mov_b32 m0, 3
	s_cmp_gt_i32 s22, s60
	s_cbranch_scc0 .LBB0_673

.Lmy_wd_6:
	s_mov_b32 m0, 0
	ds_write_b128 v165, v[144:147]
	ds_write_b128 v178, v[140:143] offset:18432
	ds_write_b128 v179, v[148:151] offset:18432

.LBB0_682:
	s_cmp_gt_u32 s52, 1
	s_cselect_b64 s[18:19], -1, 0
	s_cmp_lt_u32 s52, 2
	s_cselect_b64 s[16:17], -1, 0
	s_and_b64 vcc, exec, s[16:17]
	v_add_u32_e32 v9, s64, v162
	v_add_u32_e32 v8, s64, v163
	v_add_u32_e32 v7, s64, v164
	s_cbranch_vccnz .LBB0_689
	v_add_u32_e32 v4, 0xffffff80, v9
	v_mad_i64_i32 v[10:11], s[20:21], v4, s81, v[156:157]
	v_add_u32_e32 v4, 0xffffff80, v8
	v_mad_i64_i32 v[12:13], s[20:21], v4, s81, v[158:159]
	v_add_u32_e32 v4, 0xffffff80, v7
	global_load_dwordx4 v[144:147], v[10:11], off
	global_load_dwordx4 v[140:143], v[12:13], off
	v_mad_i64_i32 v[10:11], s[20:21], v4, s81, v[160:161]
	global_load_dwordx4 v[148:151], v[10:11], off
	s_mov_b32 m0, 3
	s_cmp_gt_i32 s52, s60
	s_cbranch_scc0 .LBB0_690

.LBB0_685:
	v_add_u32_e32 v4, s62, v165
	s_cmp_eq_u32 m0, 0
	s_cbranch_scc1 .Lmy_wz_7
	s_waitcnt vmcnt(3)
	s_branch .Lmy_wd_7

.Lmy_wd_7:
	s_mov_b32 m0, 0
	ds_write_b128 v4, v[128:131]
	ds_write_b128 v1, v[132:135] offset:18432
	ds_write_b128 v2, v[136:139] offset:18432
.LBB0_686:
	s_cmp_lt_u32 s52, 3
	s_waitcnt lgkmcnt(0)
	s_barrier
	s_cbranch_scc1 .LBB0_692
	v_add_u32_e32 v4, 0xffffff40, v9
	v_mad_i64_i32 v[10:11], s[20:21], v4, s81, v[156:157]
	v_add_u32_e32 v4, 0xffffff40, v8
	v_mad_i64_i32 v[8:9], s[20:21], v4, s81, v[158:159]
	v_add_u32_e32 v4, 0xffffff40, v7
	global_load_dwordx4 v[128:131], v[10:11], off
	global_load_dwordx4 v[132:135], v[8:9], off
	v_mad_i64_i32 v[8:9], s[20:21], v4, s81, v[160:161]
	global_load_dwordx4 v[136:139], v[8:9], off
	s_mov_b32 m0, 3
	s_add_i32 s20, s52, -1
	s_cmp_gt_i32 s20, s60
	s_cbranch_scc0 .LBB0_693

.LBB0_705:
	v_add_u32_e32 v4, s4, v165
	s_cmp_eq_u32 m0, 0
	s_cbranch_scc1 .Lmy_wz_8
	s_waitcnt vmcnt(3)
	s_branch .Lmy_wd_8

.Lmy_wd_8:
	s_mov_b32 m0, 0
	ds_write_b128 v4, v[144:147]
	ds_write_b128 v3, v[140:143] offset:18432
	ds_write_b128 v6, v[148:151] offset:18432
	s_branch .LBB0_681

.LBB0_709:
	s_add_i32 s21, s5, 1
	s_cmp_gt_i32 s21, 1
	s_cselect_b64 s[14:15], -1, 0
	s_cmp_lt_i32 s21, 2
	v_add_u32_e32 v2, s53, v235
	v_add_u32_e32 v1, s53, v236
	v_add_u32_e32 v0, s53, v237
	s_cbranch_scc1 .LBB0_719
	v_add_u32_e32 v3, 0xffffff40, v2
	v_mad_i64_i32 v[6:7], s[16:17], v3, s81, v[156:157]
	v_add_u32_e32 v3, 0xffffff40, v1
	v_mad_i64_i32 v[8:9], s[16:17], v3, s81, v[158:159]
	v_add_u32_e32 v3, 0xffffff40, v0
	global_load_dwordx4 v[144:147], v[6:7], off offset:128
	global_load_dwordx4 v[140:143], v[8:9], off
	v_mad_i64_i32 v[6:7], s[16:17], v3, s81, v[160:161]
	global_load_dwordx4 v[148:151], v[6:7], off
	s_mov_b32 m0, 3
	s_add_i32 s7, s4, s5
	s_cmp_gt_i32 s21, s22
	s_cbranch_scc0 .LBB0_720

.Lmy_wd_9:
	s_mov_b32 m0, 0
	ds_write_b128 v221, v[128:131] offset:9216
	ds_write_b128 v231, v[132:135] offset:38912
	ds_write_b128 v232, v[136:139] offset:38912
.LBB0_713:
	s_cmp_lt_i32 s21, 3
	s_waitcnt lgkmcnt(0)
	s_barrier
	s_cbranch_scc1 .LBB0_725
	v_add_u32_e32 v2, 0xffffff00, v2
	v_add_u32_e32 v1, 0xffffff00, v1
	v_add_u32_e32 v0, 0xffffff00, v0
	v_mad_i64_i32 v[2:3], s[16:17], v2, s81, v[156:157]
	v_mad_i64_i32 v[6:7], s[16:17], v1, s81, v[158:159]
	v_mad_i64_i32 v[0:1], s[16:17], v0, s81, v[160:161]
	global_load_dwordx4 v[128:131], v[2:3], off offset:128
	global_load_dwordx4 v[132:135], v[6:7], off
	global_load_dwordx4 v[136:139], v[0:1], off
	s_mov_b32 m0, 3
	s_cmp_gt_i32 s5, s22
	s_cbranch_scc0 .LBB0_726

.Lmy_wd_10:
	s_mov_b32 m0, 0
	ds_write_b128 v221, v[144:147]
	ds_write_b128 v231, v[140:143] offset:18432
	ds_write_b128 v232, v[148:151] offset:18432

.LBB0_735:
	s_cmp_gt_u32 s7, 1
	s_cselect_b64 s[16:17], -1, 0
	s_cmp_lt_u32 s7, 2
	s_cselect_b64 s[14:15], -1, 0
	s_and_b64 vcc, exec, s[14:15]
	v_add_u32_e32 v9, s47, v218
	v_add_u32_e32 v8, s47, v219
	v_add_u32_e32 v7, s47, v220
	s_cbranch_vccnz .LBB0_742
	v_add_u32_e32 v4, 0xffffff80, v9
	v_mad_i64_i32 v[10:11], s[18:19], v4, s81, v[156:157]
	v_add_u32_e32 v4, 0xffffff80, v8
	v_mad_i64_i32 v[12:13], s[18:19], v4, s81, v[158:159]
	v_add_u32_e32 v4, 0xffffff80, v7
	global_load_dwordx4 v[144:147], v[10:11], off offset:128
	global_load_dwordx4 v[140:143], v[12:13], off
	v_mad_i64_i32 v[10:11], s[18:19], v4, s81, v[160:161]
	global_load_dwordx4 v[148:151], v[10:11], off
	s_mov_b32 m0, 3
	s_cmp_gt_i32 s7, s22
	s_cbranch_scc0 .LBB0_743

.LBB0_738:
	v_add_u32_e32 v4, s23, v221
	s_cmp_eq_u32 m0, 0
	s_cbranch_scc1 .Lmy_wz_11
	s_waitcnt vmcnt(3)
	s_branch .Lmy_wd_11

.LBB0_739:
	s_cmp_lt_u32 s7, 3
	s_waitcnt lgkmcnt(0)
	s_barrier
	s_cbranch_scc1 .LBB0_745
	v_add_u32_e32 v4, 0xffffff40, v9
	v_mad_i64_i32 v[10:11], s[18:19], v4, s81, v[156:157]
	v_add_u32_e32 v4, 0xffffff40, v8
	v_mad_i64_i32 v[8:9], s[18:19], v4, s81, v[158:159]
	v_add_u32_e32 v4, 0xffffff40, v7
	global_load_dwordx4 v[128:131], v[10:11], off offset:128
	global_load_dwordx4 v[132:135], v[8:9], off
	v_mad_i64_i32 v[8:9], s[18:19], v4, s81, v[160:161]
	global_load_dwordx4 v[136:139], v[8:9], off
	s_mov_b32 m0, 3
	s_add_i32 s18, s7, -1
	s_cmp_gt_i32 s18, s22
	s_cbranch_scc0 .LBB0_746

.LBB0_758:
	v_add_u32_e32 v4, s4, v221
	s_cmp_eq_u32 m0, 0
	s_cbranch_scc1 .Lmy_wz_12
	s_waitcnt vmcnt(3)
	s_branch .Lmy_wd_12

.LBB0_763:
	s_cmp_gt_u32 s92, 1
	s_cselect_b64 s[14:15], -1, 0
	s_cmp_lt_u32 s92, 2
	s_cselect_b64 s[40:41], -1, 0
	s_and_b64 vcc, exec, s[40:41]
	s_cbranch_vccnz .LBB0_770
	s_lshl_b32 s4, s92, 6
	s_add_i32 s16, s4, 0xffffff80
	v_add_u32_e32 v4, s16, v177
	v_mad_i64_i32 v[0:1], s[4:5], v4, s81, v[146:147]
	v_add_u32_e32 v6, s16, v178
	v_mad_i64_i32 v[2:3], s[4:5], v6, s81, v[148:149]
	global_load_dwordx4 v[128:131], v[0:1], off
	global_load_dwordx4 v[132:135], v[2:3], off
	v_mad_i64_i32 v[0:1], s[4:5], v4, s81, v[150:151]
	v_mad_i64_i32 v[2:3], s[4:5], v6, s81, v[154:155]
	global_load_dwordx4 v[136:139], v[0:1], off
	global_load_dwordx4 v[140:143], v[2:3], off
	s_mov_b32 m0, 4
	s_cmp_gt_i32 s92, s84
	s_cbranch_scc0 .LBB0_771

.Lmy_wd_15:
	s_mov_b32 m0, 0
	ds_write_b128 v210, v[112:115]
	ds_write_b128 v211, v[116:119]
	ds_write_b128 v219, v[120:123] offset:34816
	ds_write_b128 v220, v[124:127] offset:34816
.LBB0_767:
	s_cmp_lt_u32 s92, 3
	s_waitcnt lgkmcnt(0)
	s_barrier
	s_cbranch_scc1 .LBB0_971
	s_lshl_b32 s4, s92, 6
	s_add_i32 s16, s4, 0xffffff40
	v_add_u32_e32 v4, s16, v177
	v_mad_i64_i32 v[0:1], s[4:5], v4, s81, v[146:147]
	v_add_u32_e32 v6, s16, v178
	v_mad_i64_i32 v[2:3], s[4:5], v6, s81, v[148:149]
	global_load_dwordx4 v[112:115], v[0:1], off
	global_load_dwordx4 v[116:119], v[2:3], off
	v_mad_i64_i32 v[0:1], s[4:5], v4, s81, v[150:151]
	v_mad_i64_i32 v[2:3], s[4:5], v6, s81, v[154:155]
	global_load_dwordx4 v[120:123], v[0:1], off
	global_load_dwordx4 v[124:127], v[2:3], off
	s_mov_b32 m0, 4
	s_add_i32 s4, s92, -1
	s_cmp_gt_i32 s4, s84
	s_cbranch_scc0 .LBB0_972

.Lmy_wd_16:
	s_mov_b32 m0, 0
	ds_write_b128 v221, v[128:131]
	ds_write_b128 v222, v[132:135]
	ds_write_b128 v208, v[136:139] offset:34816
	ds_write_b128 v209, v[140:143] offset:34816
	s_branch .LBB0_762
